# v64 with the sentinel poll trimmed: each wave polls only the 192 LDS lines it reads itself (3 ds_read2 instead of 6, half the VALU)
# speedup vs baseline: 1.0121x; 1.0051x over previous
.Lgin_k:
	s_setprio 2
	s_waitcnt vmcnt(0)
	s_barrier
	v_and_b32_e32 v128, 63, v193
	v_and_b32_e32 v129, 15, v193
	v_lshlrev_b32_e32 v128, 7, v128
	v_lshl_add_u32 v128, v129, 2, v128
	v_bfe_u32 v129, v193, 7, 1
	v_lshl_add_u32 v130, v129, 14, v128
	v_add_u32_e32 v131, 8192, v130
	v_bfe_u32 v129, v193, 6, 1
	v_lshl_add_u32 v132, v129, 13, v128
	v_add_u32_e32 v133, 32768, v132
	s_mov_b32 s28, 64
.Lgin_poll:
	ds_read2_b32 v[148:149], v130 offset1:16
	ds_read2_b32 v[150:151], v131 offset1:16
	ds_read2_b32 v[152:153], v133 offset1:16
	s_waitcnt lgkmcnt(2)
	v_xor_b32_e32 v148, v148, v130
	v_xor_b32_e32 v149, v149, v130
	v_min_u32_e32 v148, v148, v149
	s_waitcnt lgkmcnt(1)
	v_xor_b32_e32 v150, v150, v131
	v_xor_b32_e32 v151, v151, v131
	v_min_u32_e32 v150, v150, v151
	s_waitcnt lgkmcnt(0)
	v_xor_b32_e32 v152, v152, v132
	v_xor_b32_e32 v153, v153, v132
	v_min_u32_e32 v152, v152, v153
	v_min3_u32 v148, v148, v150, v152
	v_cmp_eq_u32_e32 vcc, 0, v148
	s_cbranch_vccz .Lgin_pollok
	s_sub_u32 s28, s28, 1
	s_cmp_lg_u32 s28, 0
	s_cbranch_scc1 .Lgin_poll

.Lgin_nodma:
	s_setprio 0
	v_mfma_f32_32x32x16_bf16 v[0:15], v[216:219], v[128:131], v[0:15]
	v_mfma_f32_32x32x16_bf16 v[16:31], v[232:235], v[128:131], v[16:31]
	v_mfma_f32_32x32x16_bf16 v[32:47], v[216:219], v[148:151], v[32:47]
	v_mfma_f32_32x32x16_bf16 v[48:63], v[232:235], v[148:151], v[48:63]
	v_mfma_f32_32x32x16_bf16 v[64:79], v[216:219], v[164:167], v[64:79]
	v_mfma_f32_32x32x16_bf16 v[80:95], v[232:235], v[164:167], v[80:95]
	v_mfma_f32_32x32x16_bf16 v[96:111], v[216:219], v[180:183], v[96:111]
	v_mfma_f32_32x32x16_bf16 v[112:127], v[232:235], v[180:183], v[112:127]
	v_mfma_f32_32x32x16_bf16 v[0:15], v[220:223], v[132:135], v[0:15]
	v_mfma_f32_32x32x16_bf16 v[16:31], v[236:239], v[132:135], v[16:31]
	v_mfma_f32_32x32x16_bf16 v[32:47], v[220:223], v[152:155], v[32:47]
	v_mfma_f32_32x32x16_bf16 v[48:63], v[236:239], v[152:155], v[48:63]
	v_mfma_f32_32x32x16_bf16 v[64:79], v[220:223], v[168:171], v[64:79]
	v_mfma_f32_32x32x16_bf16 v[80:95], v[236:239], v[168:171], v[80:95]
	v_mfma_f32_32x32x16_bf16 v[96:111], v[220:223], v[184:187], v[96:111]
	v_mfma_f32_32x32x16_bf16 v[112:127], v[236:239], v[184:187], v[112:127]
	v_mfma_f32_32x32x16_bf16 v[0:15], v[224:227], v[136:139], v[0:15]
	v_mfma_f32_32x32x16_bf16 v[16:31], v[240:243], v[136:139], v[16:31]
	v_mfma_f32_32x32x16_bf16 v[32:47], v[224:227], v[156:159], v[32:47]
	v_mfma_f32_32x32x16_bf16 v[48:63], v[240:243], v[156:159], v[48:63]
	v_mfma_f32_32x32x16_bf16 v[64:79], v[224:227], v[172:175], v[64:79]
	v_mfma_f32_32x32x16_bf16 v[80:95], v[240:243], v[172:175], v[80:95]
	v_mfma_f32_32x32x16_bf16 v[96:111], v[224:227], v[188:191], v[96:111]
	v_mfma_f32_32x32x16_bf16 v[112:127], v[240:243], v[188:191], v[112:127]
	v_mfma_f32_32x32x16_bf16 v[0:15], v[228:231], v[140:143], v[0:15]
	v_mfma_f32_32x32x16_bf16 v[16:31], v[244:247], v[140:143], v[16:31]
	v_mfma_f32_32x32x16_bf16 v[32:47], v[228:231], v[160:163], v[32:47]
	v_mfma_f32_32x32x16_bf16 v[48:63], v[244:247], v[160:163], v[48:63]
	v_mfma_f32_32x32x16_bf16 v[64:79], v[228:231], v[176:179], v[64:79]
	v_mfma_f32_32x32x16_bf16 v[80:95], v[244:247], v[176:179], v[80:95]
	v_mfma_f32_32x32x16_bf16 v[96:111], v[228:231], v[212:215], v[96:111]
	v_mfma_f32_32x32x16_bf16 v[112:127], v[244:247], v[212:215], v[112:127]
